# G2 state scan: next chunk pair's loads issued before the current pair is consumed (two register sets)
# speedup vs baseline: 1.0068x; 1.0068x over previous
; __device__ __forceinline__ float bf_lo(unsigned u) { return __uint_as_float(u << 16); }
; __device__ __forceinline__ float bf_hi(unsigned u) { return __uint_as_float(u & 0xffff0000u); }
; __device__ __forceinline__ int vblk() { return (int)blockIdx.x * 2 + half_id(); }
; __device__ __forceinline__ int vgrid() { return (int)gridDim.x * 2; }
; __device__ void phaseG2(const Params& p) {
;     ...
;     for (int idx = vblk() * NTHREADS + (int)(threadIdx.x & 255); idx < 32 * 256 * 16; idx += vgrid() * NTHREADS) {
;         const int d8 = idx & 15, e = (idx >> 4) & 255, bh = idx >> 12;
;         float st[8];
; #pragma unroll
;         for (int j = 0; j < 8; j++) st[j] = 0.f;
;         for (int c = 0; c < 32; c++) {
;             const int task = bh * 32 + c;
;             u32x4* ptr = (u32x4*)(L + ((size_t)task * 256 + e) * 128 + d8 * 8);
;             const u32x4 lv = *ptr;
;             const f32x4 d0 = *(const f32x4*)(dec + task * 128 + d8 * 8), d1 = *(const f32x4*)(dec + task * 128 + d8 * 8 + 4);
;             *ptr = (u32x4){pack2(st[0], st[1]), pack2(st[2], st[3]), pack2(st[4], st[5]), pack2(st[6], st[7])};
;             st[0] = d0[0] * st[0] + bf_lo(lv.x); st[1] = d0[1] * st[1] + bf_hi(lv.x);
;             st[2] = d0[2] * st[2] + bf_lo(lv.y); st[3] = d0[3] * st[3] + bf_hi(lv.y);
;             st[4] = d1[0] * st[4] + bf_lo(lv.z); st[5] = d1[1] * st[5] + bf_hi(lv.z);
;             st[6] = d1[2] * st[6] + bf_lo(lv.w); st[7] = d1[3] * st[7] + bf_hi(lv.w);
;         }
;     }
.LBB0_450:
	v_lshlrev_b32_e32 v0, 1, v13
	v_and_b32_e32 v4, 0xff00, v0
	v_and_b32_e32 v5, 0xf0, v0
	v_ashrrev_i32_e32 v0, 7, v12
	v_and_b32_e32 v2, 0xffffffe0, v0
	v_and_b32_e32 v0, 0xfffff000, v12
	v_ashrrev_i32_e32 v1, 31, v0
	v_lshlrev_b32_e32 v3, 2, v13
	v_lshlrev_b64 v[0:1], 2, v[0:1]
	v_and_or_b32 v0, v3, s2, v0
	v_ashrrev_i32_e32 v3, 31, v2
	v_lshlrev_b64 v[2:3], 16, v[2:3]
	v_or3_b32 v2, v2, v4, v5
	v_mov_b32_e32 v4, 0
	s_waitcnt lgkmcnt(0)
	v_lshl_add_u64 v[0:1], s[6:7], 0, v[0:1]
	v_lshl_add_u64 v[2:3], s[4:5], 0, v[2:3]
	s_mov_b64 s[20:21], 0
	v_mov_b32_e32 v5, v4
	v_mov_b32_e32 v6, v4
	v_mov_b32_e32 v7, v4
	v_mov_b32_e32 v8, v4
	v_mov_b32_e32 v9, v4
	v_mov_b32_e32 v10, v4
	v_mov_b32_e32 v11, v4
	s_mov_b64 s[24:25], 0x10000
	s_mov_b64 s[26:27], 0x400
	s_mov_b32 s28, 0
	v_lshl_add_u64 v[104:105], v[0:1], 0, s[14:15]
	v_mov_b32_e32 v84, v2
	v_mov_b32_e32 v85, v3
	v_lshl_add_u64 v[86:87], v[2:3], 0, s[24:25]
	v_lshl_add_u64 v[82:83], v[2:3], 0, s[24:25]
	global_load_dwordx4 v[14:17], v[2:3], off
	global_load_dwordx4 v[22:25], v[82:83], off
	global_load_dwordx4 v[26:29], v[104:105], off
	global_load_dwordx4 v[30:33], v[104:105], off offset:16
	global_load_dwordx4 v[48:51], v[104:105], off offset:512
	global_load_dwordx4 v[34:37], v[104:105], off offset:528
	v_lshl_add_u64 v[2:3], v[2:3], 0, s[18:19]
	v_lshl_add_u64 v[82:83], v[82:83], 0, s[18:19]
	v_lshl_add_u64 v[104:105], v[104:105], 0, s[26:27]
.Lg2_loop:
	global_load_dwordx4 v[52:55], v[2:3], off
	global_load_dwordx4 v[56:59], v[82:83], off
	global_load_dwordx4 v[60:63], v[104:105], off
	global_load_dwordx4 v[64:67], v[104:105], off offset:16
	global_load_dwordx4 v[68:71], v[104:105], off offset:512
	global_load_dwordx4 v[72:75], v[104:105], off offset:528
	v_lshl_add_u64 v[2:3], v[2:3], 0, s[18:19]
	v_lshl_add_u64 v[82:83], v[82:83], 0, s[18:19]
	v_lshl_add_u64 v[104:105], v[104:105], 0, s[26:27]
	s_waitcnt vmcnt(6)
	v_lshlrev_b32_e32 v88, 16, v14
	v_and_b32_e32 v89, 0xffff0000, v14
	v_lshlrev_b32_e32 v90, 16, v15
	v_and_b32_e32 v91, 0xffff0000, v15
	v_lshlrev_b32_e32 v92, 16, v16
	v_and_b32_e32 v93, 0xffff0000, v16
	v_lshlrev_b32_e32 v94, 16, v17
	v_and_b32_e32 v95, 0xffff0000, v17
	v_cvt_pk_bf16_f32 v18, v6, v7
	v_cvt_pk_bf16_f32 v19, v8, v9
	v_cvt_pk_bf16_f32 v20, v10, v11
	v_cvt_pk_bf16_f32 v21, v4, v5
	global_store_dwordx4 v[84:85], v[18:21], off
	v_pk_fma_f32 v[6:7], v[6:7], v[26:27], v[88:89]
	v_pk_fma_f32 v[8:9], v[8:9], v[28:29], v[90:91]
	v_pk_fma_f32 v[10:11], v[10:11], v[30:31], v[92:93]
	v_pk_fma_f32 v[4:5], v[4:5], v[32:33], v[94:95]
	v_lshlrev_b32_e32 v96, 16, v22
	v_and_b32_e32 v97, 0xffff0000, v22
	v_lshlrev_b32_e32 v98, 16, v23
	v_and_b32_e32 v99, 0xffff0000, v23
	v_lshlrev_b32_e32 v100, 16, v24
	v_and_b32_e32 v101, 0xffff0000, v24
	v_lshlrev_b32_e32 v102, 16, v25
	v_and_b32_e32 v103, 0xffff0000, v25
	v_cvt_pk_bf16_f32 v76, v6, v7
	v_cvt_pk_bf16_f32 v77, v8, v9
	v_cvt_pk_bf16_f32 v78, v10, v11
	v_cvt_pk_bf16_f32 v79, v4, v5
	global_store_dwordx4 v[86:87], v[76:79], off
	v_pk_fma_f32 v[6:7], v[6:7], v[48:49], v[96:97]
	v_pk_fma_f32 v[8:9], v[8:9], v[50:51], v[98:99]
	v_pk_fma_f32 v[10:11], v[10:11], v[34:35], v[100:101]
	v_pk_fma_f32 v[4:5], v[4:5], v[36:37], v[102:103]
	v_lshl_add_u64 v[84:85], v[84:85], 0, s[18:19]
	v_lshl_add_u64 v[86:87], v[86:87], 0, s[18:19]
	s_cmp_eq_u32 s28, 7
	s_cbranch_scc1 .Lg2_last
	global_load_dwordx4 v[14:17], v[2:3], off
	global_load_dwordx4 v[22:25], v[82:83], off
	global_load_dwordx4 v[26:29], v[104:105], off
	global_load_dwordx4 v[30:33], v[104:105], off offset:16
	global_load_dwordx4 v[48:51], v[104:105], off offset:512
	global_load_dwordx4 v[34:37], v[104:105], off offset:528
	v_lshl_add_u64 v[2:3], v[2:3], 0, s[18:19]
	v_lshl_add_u64 v[82:83], v[82:83], 0, s[18:19]
	v_lshl_add_u64 v[104:105], v[104:105], 0, s[26:27]
	s_waitcnt vmcnt(6)
	s_branch .Lg2_b

; __device__ __forceinline__ float bf_lo(unsigned u) { return __uint_as_float(u << 16); }
; __device__ __forceinline__ float bf_hi(unsigned u) { return __uint_as_float(u & 0xffff0000u); }
; __device__ void phaseG2(const Params& p) {
;     ...
;         for (int c = 0; c < 32; c++) {
;             const int task = bh * 32 + c;
;             u32x4* ptr = (u32x4*)(L + ((size_t)task * 256 + e) * 128 + d8 * 8);
;             const u32x4 lv = *ptr;
;             const f32x4 d0 = *(const f32x4*)(dec + task * 128 + d8 * 8), d1 = *(const f32x4*)(dec + task * 128 + d8 * 8 + 4);
;             *ptr = (u32x4){pack2(st[0], st[1]), pack2(st[2], st[3]), pack2(st[4], st[5]), pack2(st[6], st[7])};
;             st[0] = d0[0] * st[0] + bf_lo(lv.x); st[1] = d0[1] * st[1] + bf_hi(lv.x);
;             st[2] = d0[2] * st[2] + bf_lo(lv.y); st[3] = d0[3] * st[3] + bf_hi(lv.y);
;             st[4] = d1[0] * st[4] + bf_lo(lv.z); st[5] = d1[1] * st[5] + bf_hi(lv.z);
;             st[6] = d1[2] * st[6] + bf_lo(lv.w); st[7] = d1[3] * st[7] + bf_hi(lv.w);
;         }
;     }
.Lg2_b:
	v_lshlrev_b32_e32 v88, 16, v52
	v_and_b32_e32 v89, 0xffff0000, v52
	v_lshlrev_b32_e32 v90, 16, v53
	v_and_b32_e32 v91, 0xffff0000, v53
	v_lshlrev_b32_e32 v92, 16, v54
	v_and_b32_e32 v93, 0xffff0000, v54
	v_lshlrev_b32_e32 v94, 16, v55
	v_and_b32_e32 v95, 0xffff0000, v55
	v_cvt_pk_bf16_f32 v18, v6, v7
	v_cvt_pk_bf16_f32 v19, v8, v9
	v_cvt_pk_bf16_f32 v20, v10, v11
	v_cvt_pk_bf16_f32 v21, v4, v5
	global_store_dwordx4 v[84:85], v[18:21], off
	v_pk_fma_f32 v[6:7], v[6:7], v[60:61], v[88:89]
	v_pk_fma_f32 v[8:9], v[8:9], v[62:63], v[90:91]
	v_pk_fma_f32 v[10:11], v[10:11], v[64:65], v[92:93]
	v_pk_fma_f32 v[4:5], v[4:5], v[66:67], v[94:95]
	v_lshlrev_b32_e32 v96, 16, v56
	v_and_b32_e32 v97, 0xffff0000, v56
	v_lshlrev_b32_e32 v98, 16, v57
	v_and_b32_e32 v99, 0xffff0000, v57
	v_lshlrev_b32_e32 v100, 16, v58
	v_and_b32_e32 v101, 0xffff0000, v58
	v_lshlrev_b32_e32 v102, 16, v59
	v_and_b32_e32 v103, 0xffff0000, v59
	v_cvt_pk_bf16_f32 v76, v6, v7
	v_cvt_pk_bf16_f32 v77, v8, v9
	v_cvt_pk_bf16_f32 v78, v10, v11
	v_cvt_pk_bf16_f32 v79, v4, v5
	global_store_dwordx4 v[86:87], v[76:79], off
	v_pk_fma_f32 v[6:7], v[6:7], v[68:69], v[96:97]
	v_pk_fma_f32 v[8:9], v[8:9], v[70:71], v[98:99]
	v_pk_fma_f32 v[10:11], v[10:11], v[72:73], v[100:101]
	v_pk_fma_f32 v[4:5], v[4:5], v[74:75], v[102:103]
	v_lshl_add_u64 v[84:85], v[84:85], 0, s[18:19]
	v_lshl_add_u64 v[86:87], v[86:87], 0, s[18:19]
	s_add_i32 s28, s28, 1
	s_cmp_lt_u32 s28, 8
	s_cbranch_scc1 .Lg2_loop
	v_add_u32_e32 v12, s0, v12
	v_cmp_lt_i32_e32 vcc, s23, v12
	s_or_b64 s[10:11], vcc, s[10:11]
	v_add_u32_e32 v13, s1, v13
	s_andn2_b64 exec, exec, s[10:11]
	s_cbranch_execnz .LBB0_450

; __device__ void phaseN2_task(const Params& p, int task, char* lds, bf16_t* ydst, int ystride, volatile unsigned* uex, char* ldsb) {
;     ...
;     {
;         const int lo = (t0 & ~31) - 511;
;         const int jb0 = lo > 0 ? (lo >> 6) : 0;
;         const int kkey = t512 >> 3, kch = (t512 & 7) * 8;
;         const int vd = t512 >> 3, vch = (t512 & 7) * 8;
;         const bf16_t* vtb = (const bf16_t*)(p.ws + OFF_VT) + ((size_t)(b * 2 + g) * 64 + vd) * SEQ + vch;
;         u32x4 kreg, vreg;
;         int br = 0, j = 0;
;         {
;             const bf16_t* kb = Z + (rowb + 0) * ZC + ZKS + g * 64;
;             kreg = *(const u32x4*)(kb + (size_t)kkey * ZC + kch);
;             vreg = *(const u32x4*)(vtb);
;         }
;         f32x4 O[2][4];
;         float m[2] = {-1e30f, -1e30f}, l[2] = {0.f, 0.f};
; #pragma unroll
;         for (int x = 0; x < 2; x++)
; #pragma unroll
;             for (int dt = 0; dt < 4; dt++) O[x][dt] = (f32x4){0.f, 0.f, 0.f, 0.f};
.LBB0_616:
	s_or_b64 exec, exec, s[4:5]
	s_lshl_b32 s4, 2, s76
	s_add_i32 s4, s4, -1
	s_cmp_lg_u32 s76, 31
	s_cselect_b32 s10, s4, -2
	s_add_i32 s4, s1, 0xfffffe01
	s_ashr_i32 s11, s4, 6
	s_lshl_b32 s0, s0, 18
	s_add_u32 s4, s92, s0
	v_ashrrev_i32_e32 v49, 31, v48
	s_addc_u32 s5, s93, 0
	s_mul_i32 s0, s88, 0x2700
	v_lshlrev_b64 v[16:17], 12, v[48:49]
	s_add_u32 s0, s90, s0
	v_lshlrev_b32_e32 v25, 3, v124
	v_lshl_add_u64 v[16:17], s[4:5], 0, v[16:17]
	s_addc_u32 s5, s91, 0
	s_lshl_b32 s12, s89, 6
	s_lshl_b32 s4, s89, 7
	v_and_b32_e32 v34, 56, v25
	s_add_u32 s4, s0, s4
	s_movk_i32 s0, 0x1380
	v_lshlrev_b32_e32 v88, 1, v34
	s_addc_u32 s5, s5, 0
	v_mad_i64_i32 v[94:95], s[6:7], v48, s0, 0
	v_lshl_add_u64 v[36:37], v[16:17], 0, v[88:89]
	v_lshl_add_u64 v[16:17], v[94:95], 1, s[4:5]
	v_lshl_add_u64 v[16:17], v[16:17], 0, v[88:89]
	s_movk_i32 s0, 0x2000
	v_add_co_u32_e32 v16, vcc, s0, v16
	s_mov_b32 s0, 0xf800000
	s_nop 0
	v_addc_co_u32_e32 v17, vcc, 0, v17, vcc
	v_mov_b32_e32 v93, v91
	v_add_co_u32_e32 v20, vcc, s0, v36
	s_waitcnt lgkmcnt(0)
	s_barrier
	flat_load_dword v33, v[90:91] sc0 sc1
	s_waitcnt vmcnt(0)
	flat_load_dword v35, v[92:93] sc0 sc1
	s_waitcnt vmcnt(0)
	v_addc_co_u32_e32 v21, vcc, 0, v37, vcc
	global_load_dwordx4 v[16:19], v[16:17], off offset:512
	s_nop 0
	global_load_dwordx4 v[20:23], v[20:21], off
	v_and_b32_e32 v26, 7, v124
	v_lshlrev_b32_e32 v38, 7, v48
	v_bitop3_b32 v27, v75, v124, 7 bitop3:0x78
	v_bitop3_b32 v40, v25, 56, v124 bitop3:0x48
	v_bitop3_b32 v42, v75, v26, 4 bitop3:0x36
	v_lshlrev_b32_e32 v39, 4, v48
	v_lshlrev_b32_e32 v28, 4, v74
	v_lshlrev_b32_e32 v29, 1, v129
	v_mov_b32_e32 v24, 0
	v_lshlrev_b32_e32 v41, 4, v27
	v_lshl_or_b32 v136, v40, 1, v38
	v_lshlrev_b32_e32 v40, 4, v42
	s_mov_b64 s[4:5], 0xf800000
	s_cmpk_gt_i32 s1, 0x1ff
	s_mov_b32 s89, s85
	v_lshrrev_b32_e32 v93, 16, v127
	v_lshrrev_b32_e32 v133, 16, v128
	v_add_u32_e32 v134, 0xfffffe01, v126
	v_mov_b32_e32 v143, 0
	v_mov_b32_e32 v102, 0xf149f2ca
	s_mov_b64 s[8:9], 0
	v_mov_b32_e32 v103, 0xf149f2ca
	v_mov_b32_e32 v56, 0
	v_add3_u32 v135, v51, v28, v29
	v_mov_b32_e32 v25, v24
	v_mov_b32_e32 v26, v24
	v_mov_b32_e32 v27, v24
	v_mov_b32_e32 v28, v24
	v_mov_b32_e32 v29, v24
	v_mov_b32_e32 v30, v24
	v_mov_b32_e32 v31, v24
	v_mov_b32_e32 v32, v24
	v_lshlrev_b32_e32 v96, 1, v34
	v_add_u32_e32 v137, v51, v41
	v_add3_u32 v138, v38, v39, v88
	v_add_u32_e32 v139, v51, v40
	v_lshl_add_u64 v[98:99], v[36:37], 0, s[4:5]
	s_cselect_b32 s0, s11, 0
	s_lshl_b32 s84, s12, 1
	v_mov_b32_e32 v34, v24
	v_mov_b32_e32 v36, v24
	v_mov_b32_e32 v37, v24
	v_mov_b32_e32 v38, v24
	v_mov_b32_e32 v39, v24
	v_mov_b32_e32 v40, v24
	v_mov_b32_e32 v41, v24
	v_mov_b32_e32 v42, v24
	v_mov_b32_e32 v43, v24
	v_mov_b32_e32 v44, v24
	v_mov_b32_e32 v45, v24
	v_mov_b32_e32 v46, v24
	v_mov_b32_e32 v47, v24
	v_mov_b32_e32 v48, v24
	v_mov_b32_e32 v49, v24
	v_mov_b32_e32 v50, v24
	v_mov_b32_e32 v51, v24
	v_mov_b32_e32 v52, v24
	v_mov_b32_e32 v53, v24
	v_mov_b32_e32 v54, v24
	v_mov_b32_e32 v55, v24
	v_mov_b32_e32 v100, v24
	v_mov_b32_e32 v101, v24
	s_waitcnt lgkmcnt(0)
	v_bitop3_b32 v140, v35, s10, v33 bitop3:0xc8
	v_mov_b32_e32 v33, v24
	v_mov_b32_e32 v35, v24
	v_mov_b32_e32 v176, 0
	v_mov_b32_e32 v177, 0
	v_mov_b32_e32 v178, v123
	v_mov_b32_e32 v179, v123
	s_mov_b32 s34, 0
	s_mov_b32 s35, 0
	v_lshl_add_u32 v183, v94, 1, v96
	v_readfirstlane_b32 s56, v98
	v_readfirstlane_b32 s57, v99
	v_readfirstlane_b32 s54, v140
	s_nop 1
	v_subrev_u32_e32 v163, s56, v98
	v_add_u32_e32 v216, 0x4800, v135
	v_add_u32_e32 v217, 0x5000, v135
	v_add_u32_e32 v218, 0x5800, v135
	v_add_u32_e32 v219, 0x6000, v135
	s_branch .LBB0_618

; __device__ __forceinline__ f32x4 mfma16(bf16x8 a, bf16x8 b, f32x4 c) { return __builtin_amdgcn_mfma_f32_16x16x32_bf16(a, b, c, 0, 0, 0); }
; __device__ __forceinline__ void nsa_block_step(const bf16_t* Ks, const bf16_t* VT, const bf16x8 (&qf)[2][2], f32x4 (&O)[2][4], float (&m)[2], float (&l)[2],
;                                                int klo, int khi, int r, int q) {
;     f32x4 s[2][4];
; #pragma unroll
;     for (int x = 0; x < 2; x++)
; #pragma unroll
;         for (int kt = 0; kt < 4; kt++) s[x][kt] = (f32x4){0.f, 0.f, 0.f, 0.f};
; #pragma unroll
;     for (int kt = 0; kt < 4; kt++)
; #pragma unroll
;         for (int ks = 0; ks < 2; ks++) {
;             const bf16x8 kf = ld_frag(Ks + (kt * 16 + r) * 64 + (((ks * 4 + q) ^ (r & 7)) * 8));
; #pragma unroll
;             for (int x = 0; x < 2; x++) s[x][kt] = mfma16(kf, qf[x][ks], s[x][kt]);
;         }
;     if (!__all((klo <= 0) && (khi >= 63))) {
;         const int a = 4 * q - klo;
;         const unsigned range = (unsigned)(khi - klo);
;         const bool any = khi >= klo;
; #pragma unroll
;         for (int kt = 0; kt < 4; kt++)
; #pragma unroll
;             for (int j = 0; j < 4; j++) {
;                 const bool valid = any && ((unsigned)(kt * 16 + j + a) <= range);
; #pragma unroll
;                 for (int x = 0; x < 2; x++) s[x][kt][j] = valid ? s[x][kt][j] : -3.0e38f;
;             }
;     }
.Ln2_t_noload:
	s_barrier
	ds_read_b128 v[56:59], v137
	ds_read_b128 v[68:71], v139
	ds_read_b128 v[60:63], v137 offset:2048
	ds_read_b128 v[76:79], v139 offset:2048
	v_cmp_eq_u32_e32 vcc, 0, v97
	v_cmp_lt_i32_e64 s[6:7], 62, v88
	v_cmp_lt_i32_e64 s[48:49], v88, v97
	ds_read_b128 v[240:243], v137 offset:4096
	ds_read_b128 v[104:107], v139 offset:4096
	s_and_b64 s[6:7], vcc, s[6:7]
	s_or_b64 s[46:47], s[6:7], s[48:49]
	s_cmp_eq_u64 s[46:47], exec
	s_cselect_b64 s[48:49], s[48:49], 0
	ds_read_b128 v[244:247], v137 offset:6144
	ds_read_b128 v[108:111], v139 offset:6144
	v_cndmask_b32_e64 v168, v176, v123, s[48:49]
	v_cndmask_b32_e64 v169, v176, v123, s[48:49]
	v_cndmask_b32_e64 v170, v176, v123, s[48:49]
	v_cndmask_b32_e64 v171, v176, v123, s[48:49]
	v_cndmask_b32_e64 v172, v177, v123, s[48:49]
	v_cndmask_b32_e64 v173, v177, v123, s[48:49]
	v_cndmask_b32_e64 v174, v177, v123, s[48:49]
	v_cndmask_b32_e64 v175, v177, v123, s[48:49]
	s_waitcnt lgkmcnt(7)
	v_mfma_f32_16x16x32_bf16 v[64:67], v[56:59], v[0:3], v[168:171]
	v_mfma_f32_16x16x32_bf16 v[56:59], v[56:59], v[8:11], v[172:175]
	s_waitcnt lgkmcnt(6)
	v_mfma_f32_16x16x32_bf16 v[80:83], v[68:71], v[4:7], v[64:67]
	v_mfma_f32_16x16x32_bf16 v[68:71], v[68:71], v[12:15], v[56:59]
	s_waitcnt lgkmcnt(5)
	v_mfma_f32_16x16x32_bf16 v[56:59], v[60:63], v[0:3], v[168:171]
	v_mfma_f32_16x16x32_bf16 v[60:63], v[60:63], v[8:11], v[172:175]
	s_waitcnt lgkmcnt(4)
	v_mfma_f32_16x16x32_bf16 v[72:75], v[76:79], v[4:7], v[56:59]
	v_mfma_f32_16x16x32_bf16 v[64:67], v[76:79], v[12:15], v[60:63]
	s_waitcnt lgkmcnt(3)
	v_mfma_f32_16x16x32_bf16 v[60:63], v[240:243], v[0:3], v[168:171]
	v_mfma_f32_16x16x32_bf16 v[56:59], v[240:243], v[8:11], v[172:175]
	s_waitcnt lgkmcnt(2)
	v_mfma_f32_16x16x32_bf16 v[84:87], v[104:107], v[4:7], v[60:63]
	v_mfma_f32_16x16x32_bf16 v[60:63], v[104:107], v[12:15], v[56:59]
	s_waitcnt lgkmcnt(1)
	v_mfma_f32_16x16x32_bf16 v[56:59], v[244:247], v[0:3], v[168:171]
	v_mfma_f32_16x16x32_bf16 v[104:107], v[244:247], v[8:11], v[172:175]
	s_waitcnt lgkmcnt(0)
	v_mfma_f32_16x16x32_bf16 v[76:79], v[108:111], v[4:7], v[56:59]
	v_mfma_f32_16x16x32_bf16 v[56:59], v[108:111], v[12:15], v[104:107]
	s_cmp_eq_u64 s[46:47], exec
	s_cbranch_scc1 .LBB0_628
	s_nop 1
	v_min_i32_e32 v88, 63, v88
	v_sub_u32_e32 v104, v88, v97
	v_cmp_ge_i32_e32 vcc, v88, v97
	v_sub_u32_e32 v88, v129, v97
	v_cmp_le_u32_e64 s[6:7], v88, v104
	s_and_b64 s[6:7], vcc, s[6:7]
	v_add_u32_e32 v97, 1, v88
	v_cndmask_b32_e64 v80, v123, v80, s[6:7]
	v_cndmask_b32_e64 v68, v123, v68, s[6:7]
	v_cmp_le_u32_e64 s[6:7], v97, v104
	s_and_b64 s[6:7], vcc, s[6:7]
	v_add_u32_e32 v97, 2, v88
	v_cndmask_b32_e64 v81, v123, v81, s[6:7]
	v_cndmask_b32_e64 v69, v123, v69, s[6:7]
	v_cmp_le_u32_e64 s[6:7], v97, v104
	s_and_b64 s[6:7], vcc, s[6:7]
	v_add_u32_e32 v97, 3, v88
	v_cndmask_b32_e64 v82, v123, v82, s[6:7]
	v_cndmask_b32_e64 v70, v123, v70, s[6:7]
	v_cmp_le_u32_e64 s[6:7], v97, v104
	s_and_b64 s[6:7], vcc, s[6:7]
	v_add_u32_e32 v97, 16, v88
	v_cndmask_b32_e64 v83, v123, v83, s[6:7]
	v_cndmask_b32_e64 v71, v123, v71, s[6:7]
	v_cmp_le_u32_e64 s[6:7], v97, v104
	s_and_b64 s[6:7], vcc, s[6:7]
	v_add_u32_e32 v97, 17, v88
	v_cndmask_b32_e64 v72, v123, v72, s[6:7]
	v_cndmask_b32_e64 v64, v123, v64, s[6:7]
	v_cmp_le_u32_e64 s[6:7], v97, v104
	s_and_b64 s[6:7], vcc, s[6:7]
	v_add_u32_e32 v97, 18, v88
	v_cndmask_b32_e64 v73, v123, v73, s[6:7]
	v_cndmask_b32_e64 v65, v123, v65, s[6:7]
	v_cmp_le_u32_e64 s[6:7], v97, v104
	s_and_b64 s[6:7], vcc, s[6:7]
	v_add_u32_e32 v97, 19, v88
	v_cndmask_b32_e64 v74, v123, v74, s[6:7]
	v_cndmask_b32_e64 v66, v123, v66, s[6:7]
	v_cmp_le_u32_e64 s[6:7], v97, v104
	s_and_b64 s[6:7], vcc, s[6:7]
	v_add_u32_e32 v97, 32, v88
	v_cndmask_b32_e64 v75, v123, v75, s[6:7]
	v_cndmask_b32_e64 v67, v123, v67, s[6:7]
	v_cmp_le_u32_e64 s[6:7], v97, v104
	s_and_b64 s[6:7], vcc, s[6:7]
	v_add_u32_e32 v97, 33, v88
	v_cndmask_b32_e64 v84, v123, v84, s[6:7]
	v_cndmask_b32_e64 v60, v123, v60, s[6:7]
	v_cmp_le_u32_e64 s[6:7], v97, v104
	s_and_b64 s[6:7], vcc, s[6:7]
	v_add_u32_e32 v97, 34, v88
	v_cndmask_b32_e64 v85, v123, v85, s[6:7]
	v_cndmask_b32_e64 v61, v123, v61, s[6:7]
	v_cmp_le_u32_e64 s[6:7], v97, v104
	s_and_b64 s[6:7], vcc, s[6:7]
	v_add_u32_e32 v97, 35, v88
	v_cndmask_b32_e64 v86, v123, v86, s[6:7]
	v_cndmask_b32_e64 v62, v123, v62, s[6:7]
	v_cmp_le_u32_e64 s[6:7], v97, v104
	s_and_b64 s[6:7], vcc, s[6:7]
	v_add_u32_e32 v97, 48, v88
	v_cndmask_b32_e64 v87, v123, v87, s[6:7]
	v_cndmask_b32_e64 v63, v123, v63, s[6:7]
	v_cmp_le_u32_e64 s[6:7], v97, v104
	s_and_b64 s[6:7], vcc, s[6:7]
	v_add_u32_e32 v97, 49, v88
	v_cndmask_b32_e64 v76, v123, v76, s[6:7]
	v_cndmask_b32_e64 v56, v123, v56, s[6:7]
	v_cmp_le_u32_e64 s[6:7], v97, v104
	s_and_b64 s[6:7], vcc, s[6:7]
	v_add_u32_e32 v97, 50, v88
	v_cndmask_b32_e64 v77, v123, v77, s[6:7]
	v_cndmask_b32_e64 v57, v123, v57, s[6:7]
	v_cmp_le_u32_e64 s[6:7], v97, v104
	s_and_b64 s[6:7], vcc, s[6:7]
	v_add_u32_e32 v88, 51, v88
	v_cndmask_b32_e64 v78, v123, v78, s[6:7]
	v_cndmask_b32_e64 v58, v123, v58, s[6:7]
	v_cmp_le_u32_e64 s[6:7], v88, v104
	s_and_b64 vcc, vcc, s[6:7]
	v_cndmask_b32_e32 v79, v123, v79, vcc
	v_cndmask_b32_e32 v59, v123, v59, vcc
